# second half-step QK: no VALU block in front of its first MFMA any more (its K fragments are already loaded from the previous half-step's tail); hoisted V-fragment reads placed by register-reference sc
# speedup vs baseline: 1.0132x; 1.0026x over previous
; __device__ __forceinline__ void partialSM(f32x16& p0, f32x16& p1, float& m_reg, float& mn, float& alpha, bool rs) {
;     ...
;     const float mnL = rs ? -mn * C2 : -__builtin_inff();
;     for (int r = 0; r < 16; ++r) p0[r] = fmaf(p0[r], C2, mnL); for (int r = 0; r < 16; ++r) p1[r] = fmaf(p1[r], C2, mnL);
;     for (int r = 0; r < 16; ++r) p0[r] = __builtin_amdgcn_exp2f(p0[r]);
; }
; __device__ __forceinline__ void finishSM(f32x16& p0, f32x16& p1, float alpha, float& l_reg, bf16x8& pa0, bf16x8& pa1, bf16x8& pa2, bf16x8& pa3) {
;     for (int r = 0; r < 16; ++r) p1[r] = __builtin_amdgcn_exp2f(p1[r]);
;     float ps = 0; for (int r = 0; r < 16; ++r) ps += p0[r]; for (int r = 0; r < 16; ++r) ps += p1[r];
;     { auto rr = __builtin_amdgcn_permlane32_swap(__float_as_uint(ps), __float_as_uint(ps), false, false);
;       ps = __uint_as_float(rr[0]) + __uint_as_float(rr[1]); }
;     l_reg = l_reg * alpha + ps;
; template <int KB>
; __device__ __forceinline__ void qkt(f32x16& p0, f32x16& p1, const char* K_lds, int r32, int hi, const bf16x8* qr) {
;     p0 = f32x16{}; p1 = f32x16{};
;     const char* kb[4];
; #pragma unroll
;     for (int dd = 0; dd < 4; ++dd) kb[dd] = K_lds + KB * SHM_K + KSWZ(r32, (dd * 16 + hi * 8) * 2);
; #pragma unroll
;     for (int d0 = 0; d0 < 8; ++d0) { const char* a = kb[d0 & 3] + (d0 >> 2) * 128;
;         bf16x8 b0 = *reinterpret_cast<const bf16x8*>(a);
;         bf16x8 b1 = *reinterpret_cast<const bf16x8*>(a + 32 * 256);
;         p0 = __builtin_amdgcn_mfma_f32_32x32x16_bf16(b0, qr[d0], p0, 0, 0, 0);
;         p1 = __builtin_amdgcn_mfma_f32_32x32x16_bf16(b1, qr[d0], p1, 0, 0, 0); }
.LBB0_95:
	ds_read_b128 v[100:103], v169 offset:32768
	ds_read_b128 v[136:139], v169 offset:40960
	ds_read_b128 v[172:175], v193 offset:32768
	ds_read_b128 v[228:231], v193 offset:40960
	ds_read_b128 v[234:237], v194 offset:32768
	ds_read_b128 v[238:241], v194 offset:40960
	v_cndmask_b32_e64 v179, v148, v198, s[42:43]
	v_mul_f32_e32 v148, 0xbe0293ee, v179
	v_cndmask_b32_e64 v180, v220, v148, s[40:41]
	v_fmamk_f32 v82, v82, 0x3e0293ee, v180
	v_fmamk_f32 v83, v83, 0x3e0293ee, v180
	v_fmamk_f32 v84, v84, 0x3e0293ee, v180
	v_fmamk_f32 v85, v85, 0x3e0293ee, v180
	v_fmamk_f32 v86, v86, 0x3e0293ee, v180
	v_fmamk_f32 v87, v87, 0x3e0293ee, v180
	v_fmamk_f32 v88, v88, 0x3e0293ee, v180
	v_fmamk_f32 v89, v89, 0x3e0293ee, v180
	v_fmamk_f32 v90, v90, 0x3e0293ee, v180
	v_fmamk_f32 v91, v91, 0x3e0293ee, v180
	v_fmamk_f32 v92, v92, 0x3e0293ee, v180
	v_fmamk_f32 v93, v93, 0x3e0293ee, v180
	v_fmamk_f32 v94, v94, 0x3e0293ee, v180
	v_fmamk_f32 v95, v95, 0x3e0293ee, v180
	v_fmamk_f32 v96, v96, 0x3e0293ee, v180
	v_fmamk_f32 v97, v97, 0x3e0293ee, v180
	v_exp_f32_e32 v148, v82
	v_exp_f32_e32 v163, v83
	v_exp_f32_e32 v149, v84
	v_exp_f32_e32 v162, v85
	v_exp_f32_e32 v150, v86
	v_exp_f32_e32 v161, v87
	v_exp_f32_e32 v151, v88
	v_exp_f32_e32 v160, v89
	v_exp_f32_e32 v152, v90
	v_exp_f32_e32 v159, v91
	v_exp_f32_e32 v153, v92
	v_exp_f32_e32 v158, v93
	v_exp_f32_e32 v154, v94
	v_exp_f32_e32 v157, v95
	v_exp_f32_e32 v155, v96
	v_exp_f32_e32 v156, v97
	v_fmamk_f32 v203, v73, 0x3e0293ee, v180
	v_fmamk_f32 v204, v74, 0x3e0293ee, v180
	v_fmamk_f32 v208, v66, 0x3e0293ee, v180
	v_fmamk_f32 v209, v67, 0x3e0293ee, v180
	v_fmamk_f32 v223, v68, 0x3e0293ee, v180
	v_fmamk_f32 v224, v69, 0x3e0293ee, v180
	v_fmamk_f32 v225, v70, 0x3e0293ee, v180
	v_fmamk_f32 v198, v71, 0x3e0293ee, v180
	v_fmamk_f32 v201, v72, 0x3e0293ee, v180
	v_fmamk_f32 v205, v75, 0x3e0293ee, v180
	v_fmamk_f32 v206, v76, 0x3e0293ee, v180
	v_fmamk_f32 v207, v77, 0x3e0293ee, v180
	v_fmamk_f32 v181, v78, 0x3e0293ee, v180
	v_fmamk_f32 v226, v79, 0x3e0293ee, v180
	v_fmamk_f32 v227, v80, 0x3e0293ee, v180
	v_fmac_f32_e32 v180, 0x3e0293ee, v81
	s_waitcnt lgkmcnt(0)
	s_waitcnt lgkmcnt(5)
	v_mfma_f32_32x32x16_bf16 v[82:97], v[100:103], v[132:135], 0
	v_exp_f32_e32 v198, v198
	v_exp_f32_e32 v201, v201
	v_exp_f32_e32 v214, v204
	v_exp_f32_e32 v205, v205
	v_exp_f32_e32 v206, v206
	s_waitcnt lgkmcnt(4)
	v_mfma_f32_32x32x16_bf16 v[66:81], v[136:139], v[132:135], 0
	v_exp_f32_e32 v207, v207
	v_exp_f32_e32 v181, v181
	v_exp_f32_e32 v215, v226
	v_exp_f32_e32 v216, v227
	v_exp_f32_e32 v180, v180
	s_waitcnt lgkmcnt(3)
	v_mfma_f32_32x32x16_bf16 v[82:97], v[172:175], v[128:131], v[82:97]
	v_exp_f32_e32 v218, v209
	v_exp_f32_e32 v209, v203
	v_add_f32_e32 v203, 0, v148
	v_add_f32_e32 v203, v163, v203
	v_add_f32_e32 v203, v149, v203
	s_waitcnt lgkmcnt(2)
	v_mfma_f32_32x32x16_bf16 v[66:81], v[228:231], v[128:131], v[66:81]
	v_add_f32_e32 v203, v162, v203
	v_add_f32_e32 v203, v150, v203
	v_add_f32_e32 v203, v161, v203
	v_add_f32_e32 v203, v151, v203
	v_add_f32_e32 v203, v160, v203
	ds_read_b128 v[172:175], v195 offset:32768
	ds_read_b128 v[228:231], v195 offset:40960
	s_waitcnt lgkmcnt(3)
	v_mfma_f32_32x32x16_bf16 v[82:97], v[234:237], v[124:127], v[82:97]
	v_add_f32_e32 v203, v152, v203
	v_add_f32_e32 v203, v159, v203
	v_add_f32_e32 v203, v153, v203
	v_add_f32_e32 v203, v158, v203
	v_exp_f32_e32 v217, v208
	s_waitcnt lgkmcnt(2)
	v_mfma_f32_32x32x16_bf16 v[66:81], v[238:241], v[124:127], v[66:81]
	v_add_f32_e32 v203, v154, v203
	v_add_f32_e32 v203, v157, v203
	v_exp_f32_e32 v219, v223
	v_add_f32_e32 v203, v155, v203
	v_exp_f32_e32 v222, v224
	ds_read_b128 v[234:237], v169 offset:32896
	ds_read_b128 v[238:241], v169 offset:41088
	s_waitcnt lgkmcnt(3)
; __device__ __forceinline__ void finishSM(f32x16& p0, f32x16& p1, float alpha, float& l_reg, bf16x8& pa0, bf16x8& pa1, bf16x8& pa2, bf16x8& pa3) {
;     ...
;     PK4(p0, 0, pa0); PK4(p0, 8, pa1); PK4(p1, 0, pa2); PK4(p1, 8, pa3);
; template <int KB>
; __device__ __forceinline__ void qkt(f32x16& p0, f32x16& p1, const char* K_lds, int r32, int hi, const bf16x8* qr) {
;     p0 = f32x16{}; p1 = f32x16{};
;     const char* kb[4];
; #pragma unroll
;     for (int dd = 0; dd < 4; ++dd) kb[dd] = K_lds + KB * SHM_K + KSWZ(r32, (dd * 16 + hi * 8) * 2);
; #pragma unroll
;     for (int d0 = 0; d0 < 8; ++d0) { const char* a = kb[d0 & 3] + (d0 >> 2) * 128;
;         bf16x8 b0 = *reinterpret_cast<const bf16x8*>(a);
;         bf16x8 b1 = *reinterpret_cast<const bf16x8*>(a + 32 * 256);
;         p0 = __builtin_amdgcn_mfma_f32_32x32x16_bf16(b0, qr[d0], p0, 0, 0, 0);
;         p1 = __builtin_amdgcn_mfma_f32_32x32x16_bf16(b1, qr[d0], p1, 0, 0, 0); }
; }
	v_mfma_f32_32x32x16_bf16 v[82:97], v[172:175], v[120:123], v[82:97]
	v_add_f32_e32 v203, v156, v203
	v_exp_f32_e32 v208, v225
	v_add_f32_e32 v203, v217, v203
	v_add_f32_e32 v203, v218, v203
	v_add_f32_e32 v203, v219, v203
	s_waitcnt lgkmcnt(2)
	v_mfma_f32_32x32x16_bf16 v[66:81], v[228:231], v[120:123], v[66:81]
	v_add_f32_e32 v203, v222, v203
	v_add_f32_e32 v203, v208, v203
	v_add_f32_e32 v203, v198, v203
	v_add_f32_e32 v203, v201, v203
	v_add_f32_e32 v203, v209, v203
	ds_read_b128 v[172:175], v193 offset:32896
	ds_read_b128 v[228:231], v193 offset:41088
	s_waitcnt lgkmcnt(3)
	v_mfma_f32_32x32x16_bf16 v[82:97], v[234:237], v[116:119], v[82:97]
	v_add_f32_e32 v203, v214, v203
	v_add_f32_e32 v203, v205, v203
	v_add_f32_e32 v203, v206, v203
	v_add_f32_e32 v203, v207, v203
	v_add_f32_e32 v203, v181, v203
	s_waitcnt lgkmcnt(2)
	v_mfma_f32_32x32x16_bf16 v[66:81], v[238:241], v[116:119], v[66:81]
	v_add_f32_e32 v203, v215, v203
	v_add_f32_e32 v203, v216, v203
	v_add_f32_e32 v203, v180, v203
	v_mov_b32_e32 v204, v203
	v_cvt_pk_bf16_f32 v148, v148, v163
	ds_read_b128 v[234:237], v194 offset:32896
	ds_read_b128 v[238:241], v194 offset:41088
	s_waitcnt lgkmcnt(3)
	v_mfma_f32_32x32x16_bf16 v[82:97], v[172:175], v[112:115], v[82:97]
	v_cvt_pk_bf16_f32 v149, v149, v162
	v_cvt_pk_bf16_f32 v150, v150, v161
	v_cvt_pk_bf16_f32 v151, v151, v160
	v_cvt_pk_bf16_f32 v152, v152, v159
	v_cvt_pk_bf16_f32 v153, v153, v158
	s_waitcnt lgkmcnt(2)
	v_mfma_f32_32x32x16_bf16 v[66:81], v[228:231], v[112:115], v[66:81]
	v_cvt_pk_bf16_f32 v154, v154, v157
	v_cvt_pk_bf16_f32 v155, v155, v156
	v_cvt_pk_bf16_f32 v156, v217, v218
	v_cvt_pk_bf16_f32 v157, v219, v222
	v_cvt_pk_bf16_f32 v158, v208, v198
	ds_read_b128 v[172:175], v195 offset:32896
	ds_read_b128 v[228:231], v195 offset:41088
	s_waitcnt lgkmcnt(3)
	v_mfma_f32_32x32x16_bf16 v[82:97], v[234:237], v[108:111], v[82:97]
	v_cvt_pk_bf16_f32 v159, v201, v209
	v_cvt_pk_bf16_f32 v160, v214, v205
	v_cvt_pk_bf16_f32 v161, v206, v207
	ds_read_b64_tr_b16 v[206:207], v185 offset:0x5000
	ds_read_b64_tr_b16 v[208:209], v185 offset:0x5800
	ds_read_b64_tr_b16 v[224:225], v185 offset:0x6000
	ds_read_b64_tr_b16 v[226:227], v185 offset:0x6800
	v_cvt_pk_bf16_f32 v162, v181, v215
	v_cvt_pk_bf16_f32 v163, v216, v180
	s_waitcnt lgkmcnt(6)
	v_mfma_f32_32x32x16_bf16 v[66:81], v[238:241], v[108:111], v[66:81]
	s_nop 1
	v_permlane32_swap_b32_e32 v203, v204
	v_permlane32_swap_b32_e32 v148, v150
	v_permlane32_swap_b32_e32 v149, v151
	v_permlane32_swap_b32_e32 v152, v154
	v_permlane32_swap_b32_e32 v153, v155
	s_waitcnt lgkmcnt(5)
	v_mfma_f32_32x32x16_bf16 v[82:97], v[172:175], v[104:107], v[82:97]
	v_permlane32_swap_b32_e32 v156, v158
	v_permlane32_swap_b32_e32 v157, v159
	v_permlane32_swap_b32_e32 v160, v162
	v_permlane32_swap_b32_e32 v161, v163
	s_waitcnt lgkmcnt(4)
	v_mfma_f32_32x32x16_bf16 v[66:81], v[228:231], v[104:107], v[66:81]
	ds_read_b64_tr_b16 v[172:173], v185 offset:0x4000
	ds_read_b64_tr_b16 v[174:175], v185 offset:0x4800
	ds_read_b64_tr_b16 v[228:229], v185 offset:0x7000
	ds_read_b64_tr_b16 v[230:231], v185 offset:0x7800
	s_cmp_lt_u32 s3, s2
	s_cselect_b64 s[22:23], -1, 0
	s_cmp_ge_u32 s3, s2
	s_sub_i32 m0, 0, s100
	s_max_i32 m0, m0, 0
	s_add_i32 m0, m0, s32
	s_add_i32 m0, m0, s32
	s_sub_i32 m0, m0, 0xc000
	s_nop 0
	global_load_lds_dwordx4 v[248:249], off
	s_add_i32 m0, m0, 896
	s_nop 0
	global_load_lds_dwordx4 v[248:249], off offset:128
	v_lshl_add_u64 v[248:249], v[248:249], 0, v[250:251]
	s_add_i32 m0, s3, 1
	s_cmp_ge_u32 m0, s2
	s_cbranch_scc1 .LBB0_97
	s_max_i32 m0, s100, 0
	s_add_i32 m0, m0, s32
	s_nop 0
	global_load_lds_dwordx4 v[244:245], off
	s_add_i32 m0, m0, 0x2000
	s_nop 0
	global_load_lds_dwordx4 v[246:247], off
	v_lshl_add_u64 v[244:245], v[244:245], 0, v[250:251]
	v_lshl_add_u64 v[246:247], v[246:247], 0, v[250:251]
